# v52 + P4 tile order regrouped: each XCD round covers 16 row tiles x 2 column tiles (was 8 x 4)
# baseline (speedup 1.0000x reference)
; #define PG8_WAIT_V(n) asm volatile("s_waitcnt vmcnt(" #n ")" ::: "memory")
;     __host__ __device__ bool next(int i, Unit& u) const {
;         const long L = (long)i * G + c; if (L >= nwg) return false;
;         int wgid = (int)L; { const int q = nwg / NXCD, r = nwg % NXCD, xcd = wgid % NXCD, off = wgid / NXCD; wgid = (xcd < r ? xcd * (q + 1) : r * (q + 1) + (xcd - r) * q) + off; }
;         const int nig = wgm * nN, gid = wgid / nig, fm = gid * wgm, gsz = (nM % wgm == 0) ? wgm : ((nM - fm) < wgm ? (nM - fm) : wgm);
;         u.pm = fm + ((wgid % nig) % gsz); u.pn = (wgid % nig) / gsz; return true;
;     ...
;     int tid_ = wave * 64 + (int)__builtin_amdgcn_mbcnt_hi(~0u, __builtin_amdgcn_mbcnt_lo(~0u, 0u)); asm volatile("" : "+v"(tid_));
;     const int tid = tid_, wid = __builtin_amdgcn_readfirstlane(tid >> 6), lane = tid & 63, wr = wid >> 2, wc = wid & 3, fr = lane & 15, fq = lane >> 4;
;     const int K = g.K, nt = K / BK;
;     unsigned voffA[2], voffB[2];
; #pragma unroll
;     for (int i = 0; i < 2; ++i) { int R, C; stage_rc(tid * 16 + i * 8192, R, C); const int Rb = Epi::PERM ? ((R & ~31) + perm32(R & 31)) : R;
;         voffA[i] = A_TILED ? (unsigned)tl_off(R, C, K) * 2u : (unsigned)(R * K + C) * 2u; voffB[i] = (unsigned)tl_off(Rb, C, K) * 2u; }
;     const size_t kstepA = A_TILED ? (size_t)2048 : (size_t)(BK * 2), kstepB = 2048;
;     const size_t hstep = (size_t)HALF * K * 2;
;     const size_t tstep = 2 * hstep;
;     const unsigned ldsw = (unsigned)wid * 1024u;
;     const unsigned ldsbase = (unsigned)(size_t)lds + ldsw;
;     const int aoff = lds_byte(wr * 64 + fr, fq * 8), boff = lds_byte(wc * 32 + fr, fq * 8);
;     ...
;     const unsigned sc8w = g.sw8, sc8a = g.sa8;
;     Unit cur, nxt; int ui = 0;
;     if (!S.next(0, cur)) return;
;     f32x4 acc[2][2][4][2];
;     bf16x8 At[4][2], B0[2][2], B1[2][2];
;     const char* cA = (const char*)g.A + (size_t)cur.pm * tstep; const char* cB = (const char*)g.Bt + (size_t)cur.pn * tstep;
;     S.a_ready(cur);
;     PG8_STAGE(PG8_SB(0, 0), cB, voffB); PG8_STAGE(PG8_SB(0, 1), cB + hstep, voffB); PG8_STAGE(PG8_SA(0, 0), cA, voffA); PG8_STAGE(PG8_SA(0, 1), cA + hstep, voffA);
;     if (wr == 1) PG8_BAR;
;     PG8_WAIT_V(2); PG8_BAR;
;     PG8_STAGE(PG8_SB(1, 0), cB + kstepB, voffB); PG8_STAGE(PG8_SA(1, 0), cA + kstepA, voffA); PG8_STAGE(PG8_SB(1, 1), cB + hstep + kstepB, voffB);
.LBB0_475:
	s_cmp_lt_i32 s30, 5
	s_cselect_b64 s[0:1], -1, 0
	s_cmp_gt_i32 s31, 4
	s_cselect_b64 s[4:5], -1, 0
	s_and_b64 s[0:1], s[0:1], s[4:5]
	s_andn2_b64 vcc, exec, s[0:1]
	s_cbranch_vccnz .LBB0_549
	s_and_b32 s0, s33, 0xffffffc0
	s_waitcnt vmcnt(5)
	v_mbcnt_hi_u32_b32 v0, -1, v167
	v_add_u32_e32 v1, s0, v0
	s_mov_b32 s23, 0
	s_cmpk_gt_i32 s2, 0x15ff
	v_readfirstlane_b32 s5, v1
	s_cbranch_scc1 .LBB0_495
	s_waitcnt vmcnt(4)
	v_bfe_i32 v4, v1, 27, 1
	v_lshlrev_b32_e32 v2, 4, v1
	v_lshrrev_b32_e32 v4, 22, v4
	v_add_u32_e32 v4, v2, v4
	v_and_b32_e32 v4, 0xfffffc00, v4
	v_sub_u32_e32 v4, v2, v4
	v_ashrrev_i32_e32 v3, 31, v1
	s_waitcnt lgkmcnt(7)
	v_lshrrev_b32_e32 v5, 4, v4
	v_lshrrev_b32_e32 v3, 26, v3
	v_bitop3_b32 v4, v5, v4, 32 bitop3:0x6c
	v_add_u32_e32 v3, v1, v3
	v_ashrrev_i32_e32 v6, 31, v4
	v_ashrrev_i32_e32 v3, 6, v3
	v_lshrrev_b32_e32 v6, 26, v6
	v_lshlrev_b32_e32 v5, 3, v3
	v_add_u32_e32 v6, v4, v6
	v_and_b32_e32 v5, -16, v5
	s_waitcnt lgkmcnt(6)
	v_ashrrev_i32_e32 v7, 6, v6
	v_and_b32_e32 v6, 0xc0, v6
	v_add_u32_e32 v5, v7, v5
	v_sub_u32_e32 v4, v4, v6
	v_mov_b32_e32 v6, 1
	v_lshlrev_b32_e32 v3, 5, v3
	v_ashrrev_i16_sdwa v4, v6, sext(v4) dst_sel:DWORD dst_unused:UNUSED_PAD src0_sel:DWORD src1_sel:BYTE_0
	s_waitcnt vmcnt(3)
	v_lshlrev_b32_e32 v8, 1, v5
	s_waitcnt lgkmcnt(5)
	v_lshrrev_b32_e32 v9, 2, v5
	v_and_b32_e32 v7, 3, v7
	s_movk_i32 s0, 0xffe0
	v_and_b32_e32 v3, 32, v3
	v_bfe_i32 v4, v4, 0, 16
	v_and_b32_e32 v8, 24, v8
	v_and_b32_e32 v9, 4, v9
	v_and_or_b32 v7, v5, s0, v7
	v_or3_b32 v7, v7, v9, v8
	v_lshlrev_b32_e32 v8, 10, v5
	v_add_lshl_u32 v3, v3, v4, 4
	v_and_b32_e32 v8, 0x7fffc000, v8
	v_and_b32_e32 v3, 0xfffffe00, v3
	v_lshlrev_b32_e32 v5, 5, v5
	v_add_u32_e32 v8, v3, v8
	v_and_b32_e32 v5, 0x1e0, v5
	v_and_b32_e32 v4, 31, v4
	v_or3_b32 v5, v8, v5, v4
	v_lshlrev_b32_e32 v144, 1, v5
	v_lshlrev_b32_e32 v5, 10, v7
	v_and_b32_e32 v5, 0x7fffc000, v5
	v_add_u32_e32 v3, v5, v3
	v_lshlrev_b32_e32 v5, 5, v7
	v_and_b32_e32 v5, 0x1e0, v5
	v_or3_b32 v3, v3, v5, v4
	v_add_u32_e32 v2, 0x2000, v2
	v_lshlrev_b32_e32 v145, 1, v3
	v_ashrrev_i32_e32 v3, 31, v2
	v_lshrrev_b32_e32 v3, 22, v3
	v_add_u32_e32 v3, v2, v3
	v_ashrrev_i32_e32 v3, 10, v3
	v_mul_i32_i24_e32 v4, 0x400, v3
	v_sub_u32_e32 v2, v2, v4
	v_lshrrev_b32_e32 v4, 4, v2
	v_bitop3_b32 v2, v4, v2, 32 bitop3:0x6c
	v_ashrrev_i32_e32 v5, 31, v2
	v_lshrrev_b32_e32 v5, 26, v5
	v_lshlrev_b32_e32 v4, 3, v3
	v_add_u32_e32 v5, v2, v5
	v_and_b32_e32 v4, -16, v4
	v_ashrrev_i32_e32 v7, 6, v5
	v_add_u32_e32 v4, v7, v4
	v_and_b32_e32 v7, 3, v7
	s_ashr_i32 s12, s5, 6
	v_and_or_b32 v7, v4, s0, v7
	s_lshl_b32 s0, s12, 10
	s_ashr_i32 s49, s2, 31
	s_add_i32 s48, s0, 0
	s_lshr_b32 s0, s49, 29
	s_add_i32 s0, s2, s0
	s_ashr_i32 s4, s0, 3
	s_and_b32 s0, s0, -8
	s_ashr_i32 s1, s5, 8
	s_sub_i32 s0, s2, s0
	s_cmp_lt_i32 s0, 0
	s_movk_i32 s50, 0x2c1
	s_cselect_b32 s6, s50, 0x2c0
	s_mul_i32 s0, s0, s6
	s_add_i32 s0, s0, s4
	s_mul_hi_i32 s4, s0, 0xd1745d17
	s_lshr_b32 s6, s4, 31
	s_ashr_i32 s4, s4, 6
	s_add_i32 s6, s4, s6
	s_mul_hi_i32 s4, s0, 0x2e8ba2e9
	s_lshr_b32 s7, s4, 31
	s_ashr_i32 s4, s4, 6
	s_add_i32 s4, s4, s7
	v_and_b32_e32 v5, 0xc0, v5
	s_mulk_i32 s4, 0x160
	v_sub_u32_e32 v2, v2, v5
	s_sub_i32 s0, s0, s4
	v_lshlrev_b32_e32 v3, 5, v3
	v_ashrrev_i16_sdwa v2, v6, sext(v2) dst_sel:DWORD dst_unused:UNUSED_PAD src0_sel:DWORD src1_sel:BYTE_0
	v_lshlrev_b32_e32 v5, 1, v4
	v_lshrrev_b32_e32 v6, 2, v4
	s_sext_i32_i16 s4, s0
	v_and_b32_e32 v3, 32, v3
	v_bfe_i32 v2, v2, 0, 16
	v_and_b32_e32 v5, 24, v5
	v_and_b32_e32 v6, 4, v6
	s_bfe_u32 s4, s4, 0x3001c
	v_or3_b32 v5, v7, v6, v5
	v_lshlrev_b32_e32 v6, 10, v4
	v_add_lshl_u32 v3, v3, v2, 4
	s_add_i32 s7, s0, s4
	v_and_b32_e32 v6, 0x7fffc000, v6
	v_and_b32_e32 v3, 0xfffffe00, v3
	v_lshlrev_b32_e32 v4, 5, v4
	s_sext_i32_i16 s4, s7
	s_and_b32 s7, s7, 0xfff0
	v_add_u32_e32 v6, v3, v6
	v_and_b32_e32 v4, 0x1e0, v4
	v_and_b32_e32 v2, 31, v2
	s_sub_i32 s0, s7, s0
	v_or3_b32 v4, v6, v4, v2
	s_lshl_b32 s6, s6, 4
	s_sext_i32_i16 s0, s0
	v_lshlrev_b32_e32 v146, 1, v4
	v_lshlrev_b32_e32 v4, 10, v5
	s_lshr_b32 s4, s4, 4
	s_add_i32 s0, s6, s0
	v_and_b32_e32 v4, 0x7fffc000, v4
	s_add_i32 s22, s0, 0xff
	s_bfe_i64 s[14:15], s[4:5], 0x100000
	v_add_u32_e32 v3, v4, v3
	v_lshlrev_b32_e32 v4, 5, v5
	s_lshl_b64 s[6:7], s[22:23], 19
	s_lshl_b64 s[14:15], s[14:15], 19
	v_and_b32_e32 v4, 0x1e0, v4
	s_add_u32 s36, s56, s14
	v_or3_b32 v2, v3, v4, v2
	s_addc_u32 s37, s57, s15
	s_add_i32 s51, s48, 0x10000
	s_mov_b32 m0, s51
	s_nop 0
	global_load_lds_dwordx4 v145, s[36:37]
	s_add_i32 s54, s48, 0x12000
	v_lshlrev_b32_e32 v147, 1, v2
	s_mov_b32 m0, s54
	s_nop 0
	global_load_lds_dwordx4 v147, s[36:37]
	s_add_u32 s14, s36, 0x40000
	s_addc_u32 s15, s37, 0
	s_add_i32 s55, s48, 0x14000
	s_mov_b32 m0, s55
	s_nop 0
	global_load_lds_dwordx4 v145, s[14:15]
	s_add_i32 s58, s48, 0x16000
	s_mov_b32 m0, s58
	s_nop 0
	global_load_lds_dwordx4 v147, s[14:15]
	s_add_u32 s40, s8, s6
	s_addc_u32 s41, s9, s7
	s_mov_b32 m0, s48
	s_nop 0
	global_load_lds_dwordx4 v144, s[40:41]
	s_add_i32 s59, s48, 0x2000
	s_mov_b32 m0, s59
	s_nop 0
	global_load_lds_dwordx4 v146, s[40:41]
	s_add_u32 s14, s40, 0x40000
	s_addc_u32 s15, s41, 0
	s_add_i32 s60, s48, 0x4000
	s_mov_b32 m0, s60
	s_nop 0
	global_load_lds_dwordx4 v144, s[14:15]
	s_add_i32 s61, s48, 0x6000
	s_mov_b32 m0, s61
	s_nop 0
	global_load_lds_dwordx4 v146, s[14:15]
	s_cmp_eq_u32 s1, 1
	s_cselect_b64 s[6:7], -1, 0
	s_cmp_lg_u32 s1, 1
	s_cbranch_scc1 .LBB0_479
	s_barrier

;     __host__ __device__ bool next(int i, Unit& u) const { const bool ok = StaticOrder::next(i, u); if (ok) u.pm = nM - 1 - u.pm; return ok; }
;     __host__ __device__ bool next(int i, Unit& u) const {
;         const long L = (long)i * G + c; if (L >= nwg) return false;
;         int wgid = (int)L; { const int q = nwg / NXCD, r = nwg % NXCD, xcd = wgid % NXCD, off = wgid / NXCD; wgid = (xcd < r ? xcd * (q + 1) : r * (q + 1) + (xcd - r) * q) + off; }
;         const int nig = wgm * nN, gid = wgid / nig, fm = gid * wgm, gsz = (nM % wgm == 0) ? wgm : ((nM - fm) < wgm ? (nM - fm) : wgm);
;         u.pm = fm + ((wgid % nig) % gsz); u.pn = (wgid % nig) / gsz; return true;
;     ...
;         const bool has_next = S.next(ui + 1, nxt);
.LBB0_482:
	s_add_i32 s64, s64, 1
	s_mul_i32 s1, s64, s73
	s_mul_hi_u32 s4, s64, s3
	s_add_i32 s4, s4, s1
	s_mul_i32 s1, s64, s3
	s_add_u32 s18, s1, s2
	s_addc_u32 s19, s4, s49
	v_cmp_gt_i64_e32 vcc, s[18:19], v[134:135]
	v_cmp_lt_i64_e64 s[4:5], s[18:19], v[132:133]
	s_cbranch_vccnz .LBB0_484
	s_ashr_i32 s1, s18, 31
	s_lshr_b32 s1, s1, 29
	s_add_i32 s1, s18, s1
	s_ashr_i32 s10, s1, 3
	s_and_b32 s1, s1, -8
	s_sub_i32 s1, s18, s1
	s_cmp_lt_i32 s1, 0
	s_cselect_b32 s11, s50, 0x2c0
	s_mul_i32 s1, s1, s11
	s_add_i32 s1, s1, s10
	s_mul_hi_i32 s10, s1, 0xd1745d17
	s_lshr_b32 s11, s10, 31
	s_ashr_i32 s10, s10, 6
	s_add_i32 s11, s10, s11
	s_mul_hi_i32 s10, s1, 0x2e8ba2e9
	s_lshr_b32 s16, s10, 31
	s_ashr_i32 s10, s10, 6
	s_add_i32 s10, s10, s16
	s_mulk_i32 s10, 0x160
	s_sub_i32 s1, s1, s10
	s_sext_i32_i16 s10, s1
	s_bfe_u32 s10, s10, 0x3001c
	s_add_i32 s10, s1, s10
	s_and_b32 s17, s10, 0xfff0
	s_sub_i32 s1, s17, s1
	s_lshl_b32 s11, s11, 4
	s_sext_i32_i16 s1, s1
	s_sext_i32_i16 s16, s10
	s_add_i32 s1, s11, s1
	s_ashr_i32 s10, s16, 4
	s_add_i32 s16, s1, 0xff
